# E33: lever 7 address-arithmetic strength reduction (running row pointers) in the HGRN2 pass-1 chunk loop, on top of E28
# baseline (speedup 1.0000x reference)
; #define HG_LOAD(c_) do { _Pragma("unroll") for (int i = 0; i < 8; ++i) { const int tt = (c_) * CH + 8 * th + i; \
;       if (tt < LSC) { const int rr = rowmap(d, p0 + tt); lf[i] = Fb[(size_t)rr * 1024]; lv[i] = bf2f(Vb[(size_t)rr * 512]); if (PASS == 3) lq[i] = bf2f(Qb[(size_t)rr * 512]); else lq[i] = 0.f; } \
;       else { lf[i] = 1.f; lv[i] = 0.f; lq[i] = 0.f; } } } while (0)
; template <int PASS>
; __device__ __forceinline__ void hg_mfma_pass(const float* __restrict__ Fg, const bf16_t* __restrict__ Qg, const bf16_t* __restrict__ Vg, float* __restrict__ Sbuf, float* __restrict__ DL,
;                                              bf16_t* __restrict__ OUT, char* lds) {
;     ...
;   for (int it = blockIdx.x * 2 + hb; it < NSC * 8; it += gridDim.x * 2) {
;     const int sc = it >> 3, hd = it & 7, h = hd >> 1, d = hd & 1;
;     const float* Fb = Fg + d * 512 + h * 128 + k; const bf16_t* Qb = Qg + h * 128 + k; const bf16_t* Vb = Vg + h * 128 + k;
;     f32x4 S[8][2];
;     float* Sg = Sbuf + ((size_t)(sc * 8 + hd) * 128) * 128 + w * 32 + r16;
; #pragma unroll
;     for (int kt = 0; kt < 8; ++kt)
; #pragma unroll
;       for (int vt = 0; vt < 2; ++vt)
; #pragma unroll
;         for (int j = 0; j < 4; ++j) S[kt][vt][j] = (PASS == 1) ? 0.f : Sg[(size_t)(16 * kt + 4 * fq + j) * 128 + vt * 16];
;     float dprod = 1.f;
;     const int p0 = sc * LSC;
;     float lf[8], lq[8], lv[8];
;     ...
;     HG_LOAD(0);
.LBB0_2113:
	v_ashrrev_i32_e32 v113, 3, v68
	v_lshlrev_b32_e32 v0, 6, v68
	v_mul_lo_u32 v114, v113, s94
	v_and_b32_e32 v20, 0x180, v0
	v_add_u32_e32 v115, v114, v97
	v_lshlrev_b32_e32 v0, 1, v20
	v_mov_b32_e32 v1, v144
	v_cmp_lt_i32_e32 vcc, s81, v115
	v_lshl_add_u64 v[78:79], v[70:71], 0, v[0:1]
	v_or_b32_e32 v4, 1, v115
	v_cndmask_b32_e32 v0, v209, v210, vcc
	v_cmp_gt_i32_e32 vcc, s81, v115
	v_sub_u32_e32 v0, v0, v115
	v_cndmask_b32_e64 v0, v0, v115, s[8:9]
	v_cndmask_b32_e32 v5, v210, v209, vcc
	v_sub_u32_e32 v5, v5, v4
	v_ashrrev_i32_e32 v1, 31, v0
	v_cndmask_b32_e64 v4, v5, v4, s[8:9]
	v_lshlrev_b64 v[2:3], 10, v[0:1]
	v_ashrrev_i32_e32 v5, 31, v4
	v_lshl_add_u64 v[2:3], v[78:79], 0, v[2:3]
	v_lshlrev_b64 v[6:7], 10, v[4:5]
	v_lshl_add_u64 v[6:7], v[78:79], 0, v[6:7]
	global_load_ushort v21, v[2:3], off
	global_load_ushort v22, v[6:7], off
	v_or_b32_e32 v2, 2, v115
	v_cmp_lt_i32_e32 vcc, s81, v2
	v_or_b32_e32 v8, 3, v115
	s_movk_i32 s12, 0xfb
	v_cndmask_b32_e32 v3, v209, v210, vcc
	v_cmp_lt_i32_e32 vcc, s81, v8
	v_sub_u32_e32 v3, v3, v2
	v_cndmask_b32_e64 v2, v3, v2, s[8:9]
	v_cndmask_b32_e32 v9, v209, v210, vcc
	v_sub_u32_e32 v9, v9, v8
	v_ashrrev_i32_e32 v3, 31, v2
	v_cndmask_b32_e64 v8, v9, v8, s[8:9]
	v_lshlrev_b64 v[6:7], 10, v[2:3]
	v_ashrrev_i32_e32 v9, 31, v8
	v_lshl_add_u64 v[6:7], v[78:79], 0, v[6:7]
	v_lshlrev_b64 v[10:11], 10, v[8:9]
	v_cmp_lt_i32_e32 vcc, s12, v115
	s_movk_i32 s12, 0xfa
	v_lshl_add_u64 v[10:11], v[78:79], 0, v[10:11]
	global_load_ushort v23, v[6:7], off
	global_load_ushort v24, v[10:11], off
	v_add_u32_e32 v6, 4, v115
	v_cndmask_b32_e32 v7, v209, v210, vcc
	v_cmp_lt_i32_e32 vcc, s12, v115
	v_sub_u32_e32 v7, v7, v6
	v_add_u32_e32 v12, 5, v115
	v_cndmask_b32_e32 v13, v209, v210, vcc
	v_cndmask_b32_e64 v6, v7, v6, s[8:9]
	v_sub_u32_e32 v13, v13, v12
	v_ashrrev_i32_e32 v7, 31, v6
	v_cndmask_b32_e64 v12, v13, v12, s[8:9]
	v_lshlrev_b64 v[10:11], 10, v[6:7]
	v_ashrrev_i32_e32 v13, 31, v12
	s_movk_i32 s12, 0xf9
	v_lshl_add_u64 v[10:11], v[78:79], 0, v[10:11]
	v_lshlrev_b64 v[14:15], 10, v[12:13]
	v_cmp_lt_i32_e32 vcc, s12, v115
	v_lshl_add_u64 v[14:15], v[78:79], 0, v[14:15]
	global_load_ushort v25, v[10:11], off
	global_load_ushort v26, v[14:15], off
	v_cndmask_b32_e32 v11, v209, v210, vcc
	v_cmp_lt_i32_e32 vcc, s95, v115
	v_add_u32_e32 v10, 6, v115
	v_add_u32_e32 v16, 7, v115
	v_cndmask_b32_e32 v17, v209, v210, vcc
	v_sub_u32_e32 v11, v11, v10
	v_sub_u32_e32 v17, v17, v16
	v_cndmask_b32_e64 v10, v11, v10, s[8:9]
	v_cndmask_b32_e64 v16, v17, v16, s[8:9]
	v_ashrrev_i32_e32 v11, 31, v10
	v_ashrrev_i32_e32 v17, 31, v16
	v_lshlrev_b64 v[14:15], 10, v[10:11]
	v_lshlrev_b64 v[18:19], 10, v[16:17]
	v_lshl_add_u64 v[14:15], v[78:79], 0, v[14:15]
	v_lshl_add_u64 v[18:19], v[78:79], 0, v[18:19]
	global_load_ushort v18, v[18:19], off
	s_nop 0
	global_load_ushort v19, v[14:15], off
	v_lshlrev_b32_e32 v14, 2, v20
	v_mov_b32_e32 v15, v144
	v_lshl_add_u64 v[80:81], v[76:77], 0, v[14:15]
	v_lshlrev_b64 v[0:1], 12, v[0:1]
	v_lshl_add_u64 v[0:1], v[80:81], 0, v[0:1]
	global_load_dword v82, v[0:1], off
	v_lshlrev_b64 v[0:1], 12, v[4:5]
	v_lshl_add_u64 v[0:1], v[80:81], 0, v[0:1]
	global_load_dword v83, v[0:1], off
	v_lshlrev_b64 v[0:1], 12, v[2:3]
	v_lshl_add_u64 v[0:1], v[80:81], 0, v[0:1]
	global_load_dword v84, v[0:1], off
	v_lshlrev_b64 v[0:1], 12, v[8:9]
	v_lshl_add_u64 v[0:1], v[80:81], 0, v[0:1]
	global_load_dword v85, v[0:1], off
	v_lshlrev_b64 v[0:1], 12, v[6:7]
	v_lshl_add_u64 v[0:1], v[80:81], 0, v[0:1]
	global_load_dword v86, v[0:1], off
	v_lshlrev_b64 v[0:1], 12, v[12:13]
	v_lshl_add_u64 v[0:1], v[80:81], 0, v[0:1]
	global_load_dword v87, v[0:1], off
	v_lshlrev_b64 v[0:1], 12, v[10:11]
	v_lshl_add_u64 v[0:1], v[80:81], 0, v[0:1]
	global_load_dword v88, v[0:1], off
	v_lshlrev_b64 v[0:1], 12, v[16:17]
	v_lshl_add_u64 v[0:1], v[80:81], 0, v[0:1]
	global_load_dword v89, v[0:1], off
	v_mov_b32_e32 v0, 0
	s_waitcnt vmcnt(14)
	v_lshlrev_b32_e32 v91, 16, v22
	v_lshlrev_b32_e32 v90, 16, v21
	v_sub_u32_e32 v116, v108, v114
	v_mov_b32_e32 v111, 1.0
	s_mov_b32 s24, 0
	v_mov_b32_e32 v1, v0
	v_mov_b32_e32 v2, v0
	v_mov_b32_e32 v3, v0
	v_mov_b32_e32 v4, v0
	v_mov_b32_e32 v5, v0
	v_mov_b32_e32 v6, v0
	v_mov_b32_e32 v7, v0
	v_mov_b32_e32 v12, v0
	v_mov_b32_e32 v13, v0
	v_mov_b32_e32 v14, v0
	v_mov_b32_e32 v15, v0
	s_waitcnt vmcnt(13)
	v_lshlrev_b32_e32 v92, 16, v23
	s_waitcnt vmcnt(12)
	v_lshlrev_b32_e32 v69, 16, v24
	v_mov_b32_e32 v8, v0
	v_mov_b32_e32 v9, v0
	v_mov_b32_e32 v10, v0
	v_mov_b32_e32 v11, v0
	v_mov_b32_e32 v20, v0
	v_mov_b32_e32 v21, v0
	v_mov_b32_e32 v22, v0
	v_mov_b32_e32 v23, v0
	v_mov_b32_e32 v16, v0
	v_mov_b32_e32 v17, v0
	v_mov_b32_e32 v24, v0
	v_mov_b32_e32 v27, v0
	v_mov_b32_e32 v28, v0
	v_mov_b32_e32 v29, v0
	v_mov_b32_e32 v30, v0
	v_mov_b32_e32 v31, v0
	s_waitcnt vmcnt(11)
	v_lshlrev_b32_e32 v96, 16, v25
	s_waitcnt vmcnt(10)
	v_lshlrev_b32_e32 v93, 16, v26
	v_mov_b32_e32 v25, v0
	v_mov_b32_e32 v26, v0
	v_mov_b32_e32 v32, v0
	v_mov_b32_e32 v33, v0
	v_mov_b32_e32 v34, v0
	v_mov_b32_e32 v35, v0
	v_mov_b32_e32 v36, v0
	v_mov_b32_e32 v37, v0
	v_mov_b32_e32 v38, v0
	v_mov_b32_e32 v39, v0
	v_mov_b32_e32 v48, v0
	v_mov_b32_e32 v49, v0
	v_mov_b32_e32 v50, v0
	v_mov_b32_e32 v51, v0
	s_waitcnt vmcnt(9)
	v_lshlrev_b32_e32 v95, 16, v18
	s_waitcnt vmcnt(8)
	v_lshlrev_b32_e32 v94, 16, v19
	v_mov_b32_e32 v18, v0
	v_mov_b32_e32 v19, v0
	v_mov_b32_e32 v40, v0
	v_mov_b32_e32 v41, v0
	v_mov_b32_e32 v42, v0
	v_mov_b32_e32 v43, v0
	v_mov_b32_e32 v52, v0
	v_mov_b32_e32 v53, v0
	v_mov_b32_e32 v54, v0
	v_mov_b32_e32 v55, v0
	v_mov_b32_e32 v44, v0
	v_mov_b32_e32 v45, v0
	v_mov_b32_e32 v46, v0
	v_mov_b32_e32 v47, v0
	v_mov_b32_e32 v56, v0
	v_mov_b32_e32 v57, v0
	v_mov_b32_e32 v58, v0
	v_mov_b32_e32 v59, v0
	v_mov_b32_e32 v60, v0
	v_mov_b32_e32 v61, v0
	v_mov_b32_e32 v62, v0
	v_mov_b32_e32 v63, v0
	v_add_u32_e32 v146, 16, v115
	v_cmp_lt_i32_e32 vcc, s81, v146
	v_mov_b32_e32 v150, 0xfffffc00
	v_mov_b32_e32 v151, 0x400
	v_cndmask_b32_e32 v147, v209, v210, vcc
	v_sub_u32_e32 v147, v147, v146
	v_cndmask_b32_e64 v146, v147, v146, s[8:9]
	v_ashrrev_i32_e32 v147, 31, v146
	v_lshlrev_b64 v[178:179], 10, v[146:147]
	v_lshl_add_u64 v[178:179], v[78:79], 0, v[178:179]
	v_lshlrev_b64 v[180:181], 12, v[146:147]
	v_lshl_add_u64 v[180:181], v[80:81], 0, v[180:181]
	v_cndmask_b32_e64 v182, v150, v151, s[8:9]
	v_cndmask_b32_e64 v183, -1, 0, s[8:9]
	v_lshlrev_b64 v[184:185], 2, v[182:183]
	s_branch .LBB0_2115
; template <int PASS>
; __device__ __forceinline__ void hg_mfma_pass(const float* __restrict__ Fg, const bf16_t* __restrict__ Qg, const bf16_t* __restrict__ Vg, float* __restrict__ Sbuf, float* __restrict__ DL,
;                                              bf16_t* __restrict__ OUT, char* lds) {
;     ...
;       if (c + 1 < NCH) HG_LOAD(c + 1);
;       LDS_BARRIER();
;       bf16x8 VT[2];
; #pragma unroll
;       for (int vt = 0; vt < 2; ++vt) VT[vt] = mk8(*(const u32x2*)(sVT + (w * 32 + vt * 16 + r16) * 16 + 4 * fq), (u32x2){0u, 0u});
;       if (PASS == 3) {
;         bf16x8 Qp[4]; f32x4 A = {0.f, 0.f, 0.f, 0.f};
; #pragma unroll
;         for (int j = 0; j < 4; ++j) {
;           const char* qa = sQ + r16 * QROW + (32 * j + 4 * fq) * 2; const char* ka = sK + r16 * QROW + (32 * j + 4 * fq) * 2;
;           Qp[j] = mk8(*(const u32x2*)qa, *(const u32x2*)(qa + 32));
;           const bf16x8 Kp = mk8(*(const u32x2*)ka, *(const u32x2*)(ka + 32));
;           A = __builtin_amdgcn_mfma_f32_16x16x32_bf16(Kp, Qp[j], A, 0, 0, 0);
;         }
; #pragma unroll
;         for (int jj = 0; jj < 4; ++jj) A[jj] = (4 * fq + jj <= r16) ? A[jj] : 0.f;
;         const bf16x8 Af = mk8((u32x2){cvt2(A[0], A[1]), cvt2(A[2], A[3])}, (u32x2){0u, 0u});
; #pragma unroll
;         for (int vt = 0; vt < 2; ++vt) {
;           f32x4 O = {0.f, 0.f, 0.f, 0.f};
;           O = __builtin_amdgcn_mfma_f32_16x16x32_bf16(Af, VT[vt], O, 0, 0, 0);
; #pragma unroll
;           for (int j = 0; j < 4; ++j) {
;             const bf16x8 Sf = mk8((u32x2){cvt2(S[2 * j][vt][0], S[2 * j][vt][1]), cvt2(S[2 * j][vt][2], S[2 * j][vt][3])},
;                                   (u32x2){cvt2(S[2 * j + 1][vt][0], S[2 * j + 1][vt][1]), cvt2(S[2 * j + 1][vt][2], S[2 * j + 1][vt][3])});
;             O = __builtin_amdgcn_mfma_f32_16x16x32_bf16(Qp[j], Sf, O, 0, 0, 0);
;           }
; #pragma unroll
;           for (int jj = 0; jj < 4; ++jj) { const int tt = c * CH + 4 * fq + jj;
;             if (tt < LSC) OUT[(size_t)d * T_TOK * 512 + (size_t)rowmap(d, p0 + tt) * 512 + h * 128 + w * 32 + vt * 16 + r16] = f2bf2(O[jj]); }
;         }
;       }
; #pragma unroll
;       for (int kt = 0; kt < 8; ++kt) {
;         const bf16x8 KTf = mk8(*(const u32x2*)(sKT + (16 * kt + r16) * 16 + 4 * fq), (u32x2){0u, 0u});
;         const f32x4 dk4 = *(const f32x4*)(sD + 16 * kt + 4 * fq);
; #pragma unroll
.LBB0_2114:
	s_or_b64 exec, exec, s[12:13]
	v_lshl_add_u64 v[148:149], v[178:179], 0, v[182:183]
	v_lshl_add_u64 v[150:151], v[148:149], 0, v[182:183]
	v_lshl_add_u64 v[152:153], v[150:151], 0, v[182:183]
	v_lshl_add_u64 v[154:155], v[152:153], 0, v[182:183]
	v_lshl_add_u64 v[156:157], v[154:155], 0, v[182:183]
	v_lshl_add_u64 v[158:159], v[156:157], 0, v[182:183]
	v_lshl_add_u64 v[160:161], v[158:159], 0, v[182:183]
	v_lshl_add_u64 v[164:165], v[180:181], 0, v[184:185]
	v_lshl_add_u64 v[166:167], v[164:165], 0, v[184:185]
	v_lshl_add_u64 v[168:169], v[166:167], 0, v[184:185]
	v_lshl_add_u64 v[170:171], v[168:169], 0, v[184:185]
	v_lshl_add_u64 v[172:173], v[170:171], 0, v[184:185]
	v_lshl_add_u64 v[174:175], v[172:173], 0, v[184:185]
	v_lshl_add_u64 v[176:177], v[174:175], 0, v[184:185]
	v_mov_b32_e32 v124, v144
	global_load_ushort v92, v[178:179], off
	global_load_ushort v93, v[148:149], off
	global_load_ushort v112, v[152:153], off
	global_load_dword v82, v[180:181], off
	global_load_dword v83, v[164:165], off
	v_mov_b32_e32 v125, v144
	global_load_dword v84, v[166:167], off
	global_load_dword v85, v[168:169], off
	global_load_ushort v117, v[150:151], off
	v_mov_b32_e32 v145, v144
	s_add_i32 s24, s24, 16
	global_load_dword v86, v[170:171], off
	global_load_dword v87, v[172:173], off
	global_load_ushort v96, v[154:155], off
	global_load_ushort v134, v[156:157], off
	s_cmpk_eq_i32 s24, 0xf0
	s_waitcnt vmcnt(1)
	v_lshlrev_b32_e32 v96, 16, v96
	global_load_dword v88, v[174:175], off
	global_load_dword v89, v[176:177], off
	global_load_ushort v94, v[158:159], off
	global_load_ushort v95, v[160:161], off
	v_lshl_add_u64 v[178:179], v[182:183], 4, v[178:179]
	v_lshl_add_u64 v[180:181], v[184:185], 4, v[180:181]
	s_waitcnt lgkmcnt(0)
	s_barrier
	ds_read2st64_b64 v[118:121], v110 offset0:21 offset1:22
	v_lshlrev_b32_e32 v69, 16, v112
	v_add_u32_e32 v112, v104, v103
	ds_read2st64_b64 v[64:67], v109 offset0:29 offset1:30
	ds_read_b128 v[126:129], v112 offset:1024
	ds_read_b128 v[130:133], v112 offset:1152
	s_waitcnt lgkmcnt(3)
	v_mov_b32_e32 v122, v118
	v_mov_b32_e32 v123, v119
	s_waitcnt lgkmcnt(2)
	v_mov_b32_e32 v142, v64
	v_mov_b32_e32 v143, v65
	v_mov_b32_e32 v64, v66
	v_mov_b32_e32 v65, v67
	v_mov_b32_e32 v66, v144
	v_mov_b32_e32 v67, v144
	s_waitcnt lgkmcnt(1)
	v_pk_mul_f32 v[60:61], v[60:61], v[126:127]
	v_pk_mul_f32 v[62:63], v[62:63], v[128:129]
	v_pk_mul_f32 v[56:57], v[56:57], v[126:127]
	v_pk_mul_f32 v[58:59], v[58:59], v[128:129]
	ds_read_b128 v[126:129], v112 offset:1088
	s_waitcnt lgkmcnt(1)
	v_pk_mul_f32 v[40:41], v[40:41], v[130:131]
	v_pk_mul_f32 v[42:43], v[42:43], v[132:133]
	v_pk_mul_f32 v[48:49], v[48:49], v[130:131]
	v_pk_mul_f32 v[50:51], v[50:51], v[132:133]
	ds_read_b128 v[130:133], v112 offset:1216
	v_mfma_f32_16x16x32_bf16 v[60:63], v[122:125], v[142:145], v[60:63]
	v_mov_b32_e32 v118, v120
	v_mov_b32_e32 v119, v121
	v_mov_b32_e32 v120, v144
	v_mov_b32_e32 v121, v144
	v_mfma_f32_16x16x32_bf16 v[56:59], v[122:125], v[64:67], v[56:59]
	ds_read2st64_b64 v[122:125], v110 offset0:23 offset1:24
	s_waitcnt lgkmcnt(2)
	v_pk_mul_f32 v[44:45], v[44:45], v[126:127]
	v_pk_mul_f32 v[46:47], v[46:47], v[128:129]
	v_pk_mul_f32 v[52:53], v[52:53], v[126:127]
	v_pk_mul_f32 v[54:55], v[54:55], v[128:129]
	s_waitcnt lgkmcnt(1)
	v_pk_mul_f32 v[36:37], v[36:37], v[130:131]
	v_pk_mul_f32 v[38:39], v[38:39], v[132:133]
	v_pk_mul_f32 v[32:33], v[32:33], v[130:131]
	v_pk_mul_f32 v[34:35], v[34:35], v[132:133]
	ds_read_b128 v[130:133], v112 offset:1280
	v_mfma_f32_16x16x32_bf16 v[44:47], v[118:121], v[142:145], v[44:47]
	s_waitcnt lgkmcnt(1)
	v_mov_b32_e32 v126, v122
	v_mov_b32_e32 v127, v123
	v_mov_b32_e32 v128, v144
	v_mov_b32_e32 v129, v144
	v_mfma_f32_16x16x32_bf16 v[52:55], v[118:121], v[64:67], v[52:55]
	v_mov_b32_e32 v118, v124
	v_mov_b32_e32 v119, v125
	ds_read2st64_b64 v[122:125], v110 offset0:25 offset1:26
	s_waitcnt lgkmcnt(1)
	v_pk_mul_f32 v[28:29], v[28:29], v[130:131]
	v_pk_mul_f32 v[30:31], v[30:31], v[132:133]
	v_pk_mul_f32 v[24:25], v[24:25], v[130:131]
	v_pk_mul_f32 v[26:27], v[26:27], v[132:133]
	ds_read_b128 v[130:133], v112 offset:1344
	v_mfma_f32_16x16x32_bf16 v[40:43], v[126:129], v[142:145], v[40:43]
	v_lshlrev_b32_e32 v91, 16, v93
	v_lshlrev_b32_e32 v90, 16, v92
	v_lshlrev_b32_e32 v92, 16, v117
	v_mfma_f32_16x16x32_bf16 v[48:51], v[126:129], v[64:67], v[48:51]
	s_waitcnt lgkmcnt(1)
	v_mov_b32_e32 v126, v122
	v_mov_b32_e32 v127, v123
	s_waitcnt lgkmcnt(0)
	v_pk_mul_f32 v[16:17], v[16:17], v[130:131]
	v_mfma_f32_16x16x32_bf16 v[36:39], v[118:121], v[142:145], v[36:39]
	v_mul_f32_e64 v18, v18, v132
	v_mul_f32_e64 v19, v19, v133
	v_pk_mul_f32 v[20:21], v[20:21], v[130:131]
	v_pk_mul_f32 v[22:23], v[22:23], v[132:133]
	v_mfma_f32_16x16x32_bf16 v[32:35], v[118:121], v[64:67], v[32:35]
	v_mov_b32_e32 v118, v124
	v_mov_b32_e32 v119, v125
	ds_read2st64_b64 v[122:125], v110 offset0:27 offset1:28
	v_mfma_f32_16x16x32_bf16 v[28:31], v[126:129], v[142:145], v[28:31]
	ds_read_b128 v[130:133], v112 offset:1408
	s_waitcnt vmcnt(4)
	v_lshlrev_b32_e32 v93, 16, v134
	v_add_u32_e32 v116, -16, v116
	v_mfma_f32_16x16x32_bf16 v[24:27], v[126:129], v[64:67], v[24:27]
	s_waitcnt lgkmcnt(1)
	v_mov_b32_e32 v126, v122
	v_mov_b32_e32 v127, v123
	s_waitcnt vmcnt(0)
	v_lshlrev_b32_e32 v95, 16, v95
	v_mfma_f32_16x16x32_bf16 v[16:19], v[118:121], v[142:145], v[16:19]
	v_lshlrev_b32_e32 v94, 16, v94
	v_mfma_f32_16x16x32_bf16 v[20:23], v[118:121], v[64:67], v[20:23]
	v_mov_b32_e32 v118, v124
	v_mov_b32_e32 v119, v125
	ds_read_b128 v[122:125], v112 offset:1472
	s_waitcnt lgkmcnt(1)
	v_pk_mul_f32 v[8:9], v[8:9], v[130:131]
	v_pk_mul_f32 v[10:11], v[10:11], v[132:133]
	v_pk_mul_f32 v[12:13], v[12:13], v[130:131]
	v_pk_mul_f32 v[14:15], v[14:15], v[132:133]
	s_waitcnt lgkmcnt(0)
	v_pk_mul_f32 v[4:5], v[4:5], v[122:123]
	v_pk_mul_f32 v[6:7], v[6:7], v[124:125]
	v_pk_mul_f32 v[0:1], v[0:1], v[122:123]
	v_pk_mul_f32 v[2:3], v[2:3], v[124:125]
	v_mfma_f32_16x16x32_bf16 v[8:11], v[126:129], v[142:145], v[8:11]
	v_mfma_f32_16x16x32_bf16 v[12:15], v[126:129], v[64:67], v[12:15]
	v_mfma_f32_16x16x32_bf16 v[4:7], v[118:121], v[142:145], v[4:7]
	v_mfma_f32_16x16x32_bf16 v[0:3], v[118:121], v[64:67], v[0:3]
	s_cbranch_scc1 .LBB0_2117
